# grid barrier: acquire invalidate issued at arrival (waves parked, only sc1 polling until release) so it overlaps the wait instead of following the release
# speedup vs baseline: 1.0676x; 1.0102x over previous
; __device__ __forceinline__ void xcd_barrier_complete(unsigned* bar, unsigned x, unsigned& nloc, unsigned& nx) {
;     const unsigned G = gridDim.x * gridDim.y * gridDim.z;
;     unsigned sum, cnt, mine, sp = 0u;
;     for (;;) {
;         sum = 0u; cnt = 0u; mine = 0u;
; __device__ __forceinline__ void xcd_barrier(const XcdBarrier& b) {
;     asm volatile("s_waitcnt vmcnt(0)" ::: "memory");
;     __syncthreads();
;     if (threadIdx.x == 0) {
;         unsigned* bar = b.bar;
;         __builtin_amdgcn_s_waitcnt(0);
;         unsigned nloc = b.st[0], nx = b.st[1];
;         if (nloc == 0u) { xcd_barrier_complete(bar, b.x, nloc, nx); b.st[0] = nloc; b.st[1] = nx; }
.LBB0_65:
	s_waitcnt vmcnt(0)
	s_barrier
	s_mov_b64 s[4:5], exec
	v_readlane_b32 s6, v255, 3
	v_readlane_b32 s7, v255, 4
	s_and_b64 s[6:7], s[4:5], s[6:7]
	s_mov_b64 exec, s[6:7]
	s_cbranch_execz .LBB0_116
	s_add_i32 s6, 0, 0x20000
	v_mov_b32_e32 v0, s6
	s_waitcnt vmcnt(0) expcnt(0) lgkmcnt(0)
	buffer_inv sc1
	ds_read_b32 v2, v0
	s_add_i32 s6, 0, 0x20004
	v_mov_b32_e32 v0, s6
	ds_read_b32 v0, v0
	s_mov_b32 s13, 0
	s_waitcnt lgkmcnt(1)
	v_cmp_ne_u32_e32 vcc, 0, v2
	s_cbranch_vccnz .LBB0_80
	s_load_dword s6, s[0:1], 0xc8
	v_readlane_b32 s8, v255, 2
	v_mov_b32_e32 v1, 0
	s_waitcnt lgkmcnt(0)
	s_mul_i32 s16, s29, s6
	s_add_u32 s6, s90, 0x32200
	s_addc_u32 s7, s91, 0
	s_lshl_b32 s17, s8, 8
	s_add_u32 s18, s90, 0x32400
	s_mul_i32 s16, s16, s28
	s_addc_u32 s19, s91, 0
	s_branch .LBB0_69

; __device__ __forceinline__ unsigned xb_ld(unsigned* p)              { return __hip_atomic_load(p, __ATOMIC_RELAXED, __HIP_MEMORY_SCOPE_AGENT); }
; #define XB_SPIN(cond, bar) do { unsigned _sp = 0; while (cond) { __builtin_amdgcn_s_sleep(1); \
;     if ((++_sp & 255u) == 0u) { if (xb_ld(&(bar)[XB_TMO])) break; if (_sp > XB_SPIN_CAP) { atomicAdd(&(bar)[XB_TMO], 1u); break; } } } } while (0)
; __device__ __forceinline__ void xcd_barrier(const XcdBarrier& b) {
;     ...
;             XB_SPIN(xb_ld(&bar[XB_XGEN(b.x)]) == gen, bar);
;             __builtin_amdgcn_fence(__ATOMIC_ACQUIRE, "agent");
;             asm volatile("s_waitcnt vmcnt(0)" ::: "memory");
.LBB0_95:
	s_or_b64 exec, exec, s[10:11]
	s_waitcnt vmcnt(0)
	s_waitcnt vmcnt(0)

; __device__ __forceinline__ unsigned xb_ld(unsigned* p)              { return __hip_atomic_load(p, __ATOMIC_RELAXED, __HIP_MEMORY_SCOPE_AGENT); }
; __device__ __forceinline__ unsigned xb_add(unsigned* p, unsigned v) { return __hip_atomic_fetch_add(p, v, __ATOMIC_RELAXED, __HIP_MEMORY_SCOPE_AGENT); }
; #define XB_SPIN(cond, bar) do { unsigned _sp = 0; while (cond) { __builtin_amdgcn_s_sleep(1); \
;     if ((++_sp & 255u) == 0u) { if (xb_ld(&(bar)[XB_TMO])) break; if (_sp > XB_SPIN_CAP) { atomicAdd(&(bar)[XB_TMO], 1u); break; } } } } while (0)
; __device__ __forceinline__ void xcd_barrier(const XcdBarrier& b) {
;     ...
;             if (og + 1u == (tg + 1u) * nx) xb_add(&bar[XB_TOPGEN], 1u);
;             else XB_SPIN(xb_ld(&bar[XB_TOPGEN]) == tg, bar);
;             __builtin_amdgcn_fence(__ATOMIC_ACQUIRE, "agent");
;             xb_add(&bar[XB_XGEN(b.x)], 1u);
.LBB0_113:
	s_or_b64 exec, exec, s[8:9]
	s_mov_b64 s[8:9], exec
	v_mbcnt_lo_u32_b32 v0, s8, 0
	v_mbcnt_hi_u32_b32 v0, s9, v0
	v_cmp_eq_u32_e32 vcc, 0, v0
	s_waitcnt vmcnt(0)
	s_and_saveexec_b64 s[10:11], vcc
	s_cbranch_execz .LBB0_115
	s_bcnt1_i32_b64 s8, s[8:9]
	v_mov_b32_e32 v0, 0x2000
	v_mov_b32_e32 v1, s8
	global_atomic_add v0, v1, s[6:7] offset:1024

; __device__ __forceinline__ void xcd_barrier(const XcdBarrier& b) {
;     asm volatile("s_waitcnt vmcnt(0)" ::: "memory");
;     __syncthreads();
;     if (threadIdx.x == 0) {
;         unsigned* bar = b.bar;
;         __builtin_amdgcn_s_waitcnt(0);
;         unsigned nloc = b.st[0], nx = b.st[1];
;         if (nloc == 0u) { xcd_barrier_complete(bar, b.x, nloc, nx); b.st[0] = nloc; b.st[1] = nx; }
.LBB0_277:
	s_waitcnt vmcnt(0)
	s_waitcnt vmcnt(0)
	s_barrier
	s_mov_b64 s[4:5], exec
	v_readlane_b32 s6, v255, 3
	v_readlane_b32 s7, v255, 4
	s_and_b64 s[6:7], s[4:5], s[6:7]
	s_xor_b64 s[4:5], s[6:7], s[4:5]
	s_mov_b64 exec, s[6:7]
	s_cbranch_execz .LBB0_329
	s_add_i32 s6, 0, 0x20000
	v_mov_b32_e32 v0, s6
	s_waitcnt vmcnt(0) expcnt(0) lgkmcnt(0)
	buffer_inv sc1
	ds_read_b32 v2, v0
	s_add_i32 s6, 0, 0x20004
	v_mov_b32_e32 v0, s6
	ds_read_b32 v0, v0
	s_mov_b32 s13, 0
	s_waitcnt lgkmcnt(1)
	v_cmp_ne_u32_e32 vcc, 0, v2
	s_cbranch_vccnz .LBB0_292
	s_load_dword s6, s[0:1], 0xc8
	v_readlane_b32 s8, v255, 2
	v_mov_b32_e32 v1, 0
	s_waitcnt lgkmcnt(0)
	s_mul_i32 s16, s29, s6
	s_add_u32 s6, s90, 0x32200
	s_addc_u32 s7, s91, 0
	s_lshl_b32 s17, s8, 8
	s_add_u32 s18, s90, 0x32400
	s_mul_i32 s16, s16, s28
	s_addc_u32 s19, s91, 0
	s_branch .LBB0_281

; __device__ __forceinline__ unsigned xb_ld(unsigned* p)              { return __hip_atomic_load(p, __ATOMIC_RELAXED, __HIP_MEMORY_SCOPE_AGENT); }
; __device__ __forceinline__ unsigned xb_add(unsigned* p, unsigned v) { return __hip_atomic_fetch_add(p, v, __ATOMIC_RELAXED, __HIP_MEMORY_SCOPE_AGENT); }
; #define XB_SPIN(cond, bar) do { unsigned _sp = 0; while (cond) { __builtin_amdgcn_s_sleep(1); \
;     if ((++_sp & 255u) == 0u) { if (xb_ld(&(bar)[XB_TMO])) break; if (_sp > XB_SPIN_CAP) { atomicAdd(&(bar)[XB_TMO], 1u); break; } } } } while (0)
; __device__ __forceinline__ void xcd_barrier(const XcdBarrier& b) {
;     ...
;             if (og + 1u == (tg + 1u) * nx) xb_add(&bar[XB_TOPGEN], 1u);
;             else XB_SPIN(xb_ld(&bar[XB_TOPGEN]) == tg, bar);
;             __builtin_amdgcn_fence(__ATOMIC_ACQUIRE, "agent");
;             xb_add(&bar[XB_XGEN(b.x)], 1u);
.LBB0_325:
	s_or_b64 exec, exec, s[10:11]
	s_mov_b64 s[10:11], exec
	v_mbcnt_lo_u32_b32 v0, s10, 0
	v_mbcnt_hi_u32_b32 v0, s11, v0
	v_cmp_eq_u32_e32 vcc, 0, v0
	s_waitcnt vmcnt(0)
	s_and_saveexec_b64 s[12:13], vcc
	s_cbranch_execz .LBB0_327
	s_bcnt1_i32_b64 s10, s[10:11]
	v_mov_b32_e32 v0, 0x2000
	v_mov_b32_e32 v1, s10
	global_atomic_add v0, v1, s[6:7] offset:1024

; __device__ __forceinline__ void xcd_barrier(const XcdBarrier& b) {
;     asm volatile("s_waitcnt vmcnt(0)" ::: "memory");
;     __syncthreads();
;     if (threadIdx.x == 0) {
;         unsigned* bar = b.bar;
;         __builtin_amdgcn_s_waitcnt(0);
;         unsigned nloc = b.st[0], nx = b.st[1];
;         if (nloc == 0u) { xcd_barrier_complete(bar, b.x, nloc, nx); b.st[0] = nloc; b.st[1] = nx; }
.LBB0_475:
	s_waitcnt vmcnt(0)
	s_waitcnt vmcnt(0) lgkmcnt(0)
	s_barrier
	s_mov_b64 s[6:7], exec
	v_readlane_b32 s8, v255, 3
	v_readlane_b32 s9, v255, 4
	s_and_b64 s[8:9], s[6:7], s[8:9]
	s_mov_b64 exec, s[8:9]
	s_cbranch_execz .LBB0_526
	s_add_i32 s8, 0, 0x20000
	v_mov_b32_e32 v0, s8
	s_waitcnt vmcnt(0) expcnt(0) lgkmcnt(0)
	buffer_inv sc1
	ds_read_b32 v2, v0
	s_add_i32 s8, 0, 0x20004
	v_mov_b32_e32 v0, s8
	ds_read_b32 v0, v0
	s_mov_b32 s17, 0
	s_waitcnt lgkmcnt(1)
	v_cmp_ne_u32_e32 vcc, 0, v2
	s_cbranch_vccnz .LBB0_490
	s_load_dword s8, s[0:1], 0xc8
	v_readlane_b32 s10, v255, 2
	v_mov_b32_e32 v1, 0
	s_waitcnt lgkmcnt(0)
	s_mul_i32 s18, s29, s8
	s_add_u32 s8, s90, 0x32200
	s_addc_u32 s9, s91, 0
	s_lshl_b32 s19, s10, 8
	s_add_u32 s20, s90, 0x32400
	s_mul_i32 s18, s18, s28
	s_addc_u32 s21, s91, 0
	s_branch .LBB0_479

; __device__ __forceinline__ unsigned xb_ld(unsigned* p)              { return __hip_atomic_load(p, __ATOMIC_RELAXED, __HIP_MEMORY_SCOPE_AGENT); }
; #define XB_SPIN(cond, bar) do { unsigned _sp = 0; while (cond) { __builtin_amdgcn_s_sleep(1); \
;     if ((++_sp & 255u) == 0u) { if (xb_ld(&(bar)[XB_TMO])) break; if (_sp > XB_SPIN_CAP) { atomicAdd(&(bar)[XB_TMO], 1u); break; } } } } while (0)
; __device__ __forceinline__ void xcd_barrier(const XcdBarrier& b) {
;     ...
;             XB_SPIN(xb_ld(&bar[XB_XGEN(b.x)]) == gen, bar);
;             __builtin_amdgcn_fence(__ATOMIC_ACQUIRE, "agent");
;             asm volatile("s_waitcnt vmcnt(0)" ::: "memory");
.LBB0_505:
	s_or_b64 exec, exec, s[12:13]
	s_waitcnt vmcnt(0)
	s_waitcnt vmcnt(0)

; __device__ __forceinline__ unsigned xb_ld(unsigned* p)              { return __hip_atomic_load(p, __ATOMIC_RELAXED, __HIP_MEMORY_SCOPE_AGENT); }
; __device__ __forceinline__ unsigned xb_add(unsigned* p, unsigned v) { return __hip_atomic_fetch_add(p, v, __ATOMIC_RELAXED, __HIP_MEMORY_SCOPE_AGENT); }
; #define XB_SPIN(cond, bar) do { unsigned _sp = 0; while (cond) { __builtin_amdgcn_s_sleep(1); \
;     if ((++_sp & 255u) == 0u) { if (xb_ld(&(bar)[XB_TMO])) break; if (_sp > XB_SPIN_CAP) { atomicAdd(&(bar)[XB_TMO], 1u); break; } } } } while (0)
; __device__ __forceinline__ void xcd_barrier(const XcdBarrier& b) {
;     ...
;             if (og + 1u == (tg + 1u) * nx) xb_add(&bar[XB_TOPGEN], 1u);
;             else XB_SPIN(xb_ld(&bar[XB_TOPGEN]) == tg, bar);
;             __builtin_amdgcn_fence(__ATOMIC_ACQUIRE, "agent");
;             xb_add(&bar[XB_XGEN(b.x)], 1u);
.LBB0_523:
	s_or_b64 exec, exec, s[10:11]
	s_mov_b64 s[10:11], exec
	v_mbcnt_lo_u32_b32 v0, s10, 0
	v_mbcnt_hi_u32_b32 v0, s11, v0
	v_cmp_eq_u32_e32 vcc, 0, v0
	s_waitcnt vmcnt(0)
	s_and_saveexec_b64 s[12:13], vcc
	s_cbranch_execz .LBB0_525
	s_bcnt1_i32_b64 s10, s[10:11]
	v_mov_b32_e32 v0, 0x2000
	v_mov_b32_e32 v1, s10
	global_atomic_add v0, v1, s[8:9] offset:1024

; __device__ __forceinline__ void xcd_barrier(const XcdBarrier& b) {
;     asm volatile("s_waitcnt vmcnt(0)" ::: "memory");
;     __syncthreads();
;     if (threadIdx.x == 0) {
;         unsigned* bar = b.bar;
;         __builtin_amdgcn_s_waitcnt(0);
;         unsigned nloc = b.st[0], nx = b.st[1];
;         if (nloc == 0u) { xcd_barrier_complete(bar, b.x, nloc, nx); b.st[0] = nloc; b.st[1] = nx; }
.LBB0_552:
	s_setprio 0
	s_waitcnt vmcnt(0)
	s_waitcnt lgkmcnt(0)
	s_barrier
	s_mov_b64 s[6:7], exec
	v_readlane_b32 s8, v255, 3
	v_readlane_b32 s9, v255, 4
	s_and_b64 s[8:9], s[6:7], s[8:9]
	s_mov_b64 exec, s[8:9]
	s_cbranch_execz .LBB0_603
	s_add_i32 s8, 0, 0x20000
	v_mov_b32_e32 v0, s8
	s_waitcnt vmcnt(0) expcnt(0) lgkmcnt(0)
	buffer_inv sc1
	ds_read_b32 v2, v0
	s_add_i32 s8, 0, 0x20004
	v_mov_b32_e32 v0, s8
	ds_read_b32 v0, v0
	s_mov_b32 s15, 0
	s_waitcnt lgkmcnt(1)
	v_cmp_ne_u32_e32 vcc, 0, v2
	s_cbranch_vccnz .LBB0_567
	s_load_dword s8, s[0:1], 0xc8
	v_readlane_b32 s10, v255, 2
	v_mov_b32_e32 v1, 0
	s_waitcnt lgkmcnt(0)
	s_mul_i32 s16, s29, s8
	s_add_u32 s8, s90, 0x32200
	s_addc_u32 s9, s91, 0
	s_lshl_b32 s17, s10, 8
	s_add_u32 s18, s90, 0x32400
	s_mul_i32 s16, s16, s28
	s_addc_u32 s19, s91, 0
	s_branch .LBB0_556

; __device__ __forceinline__ void xcd_barrier(const XcdBarrier& b) {
;     asm volatile("s_waitcnt vmcnt(0)" ::: "memory");
;     __syncthreads();
;     if (threadIdx.x == 0) {
;         unsigned* bar = b.bar;
;         __builtin_amdgcn_s_waitcnt(0);
;         unsigned nloc = b.st[0], nx = b.st[1];
;         if (nloc == 0u) { xcd_barrier_complete(bar, b.x, nloc, nx); b.st[0] = nloc; b.st[1] = nx; }
.LBB0_823:
	s_waitcnt vmcnt(0)
	s_waitcnt vmcnt(63) expcnt(7) lgkmcnt(15)
	s_barrier
	s_mov_b64 s[6:7], exec
	v_readlane_b32 s8, v255, 3
	v_readlane_b32 s9, v255, 4
	s_and_b64 s[8:9], s[6:7], s[8:9]
	s_mov_b64 exec, s[8:9]
	s_cbranch_execz .LBB0_874
	s_add_i32 s8, 0, 0x20000
	v_mov_b32_e32 v0, s8
	s_waitcnt vmcnt(0) expcnt(0) lgkmcnt(0)
	buffer_inv sc1
	ds_read_b32 v2, v0
	s_add_i32 s8, 0, 0x20004
	v_mov_b32_e32 v0, s8
	ds_read_b32 v0, v0
	s_mov_b32 s15, 0
	s_waitcnt lgkmcnt(1)
	v_cmp_ne_u32_e32 vcc, 0, v2
	s_cbranch_vccnz .LBB0_838
	s_load_dword s8, s[0:1], 0xc8
	v_readlane_b32 s10, v255, 2
	v_mov_b32_e32 v1, 0
	s_waitcnt lgkmcnt(0)
	s_mul_i32 s8, s29, s8
	s_lshl_b32 s16, s8, 8
	s_add_u32 s8, s90, 0x32200
	s_addc_u32 s9, s91, 0
	s_lshl_b32 s17, s10, 8
	s_add_u32 s18, s90, 0x32400
	s_addc_u32 s19, s91, 0
	s_branch .LBB0_827

; __device__ __forceinline__ void xcd_barrier(const XcdBarrier& b) {
;     asm volatile("s_waitcnt vmcnt(0)" ::: "memory");
;     __syncthreads();
;     if (threadIdx.x == 0) {
;         unsigned* bar = b.bar;
;         __builtin_amdgcn_s_waitcnt(0);
;         unsigned nloc = b.st[0], nx = b.st[1];
;         if (nloc == 0u) { xcd_barrier_complete(bar, b.x, nloc, nx); b.st[0] = nloc; b.st[1] = nx; }
.LBB0_920:
	s_waitcnt vmcnt(0)
	s_barrier
	s_mov_b64 s[6:7], exec
	v_readlane_b32 s8, v255, 3
	v_readlane_b32 s9, v255, 4
	s_and_b64 s[8:9], s[6:7], s[8:9]
	s_xor_b64 s[6:7], s[8:9], s[6:7]
	s_mov_b64 exec, s[8:9]
	s_cbranch_execz .LBB0_972
	s_add_i32 s8, 0, 0x20000
	v_mov_b32_e32 v0, s8
	s_waitcnt vmcnt(0) expcnt(0) lgkmcnt(0)
	buffer_inv sc1
	ds_read_b32 v2, v0
	s_add_i32 s8, 0, 0x20004
	v_mov_b32_e32 v0, s8
	ds_read_b32 v0, v0
	s_mov_b32 s15, 0
	s_waitcnt lgkmcnt(1)
	v_cmp_ne_u32_e32 vcc, 0, v2
	s_cbranch_vccnz .LBB0_935
	s_load_dword s8, s[0:1], 0xc8
	v_readlane_b32 s10, v255, 2
	v_mov_b32_e32 v1, 0
	s_waitcnt lgkmcnt(0)
	s_mul_i32 s16, s29, s8
	s_add_u32 s8, s90, 0x32200
	s_addc_u32 s9, s91, 0
	s_lshl_b32 s17, s10, 8
	s_add_u32 s18, s90, 0x32400
	s_mul_i32 s16, s16, s28
	s_addc_u32 s19, s91, 0
	s_branch .LBB0_924

; __device__ __forceinline__ unsigned xb_ld(unsigned* p)              { return __hip_atomic_load(p, __ATOMIC_RELAXED, __HIP_MEMORY_SCOPE_AGENT); }
; __device__ __forceinline__ unsigned xb_add(unsigned* p, unsigned v) { return __hip_atomic_fetch_add(p, v, __ATOMIC_RELAXED, __HIP_MEMORY_SCOPE_AGENT); }
; #define XB_SPIN(cond, bar) do { unsigned _sp = 0; while (cond) { __builtin_amdgcn_s_sleep(1); \
;     if ((++_sp & 255u) == 0u) { if (xb_ld(&(bar)[XB_TMO])) break; if (_sp > XB_SPIN_CAP) { atomicAdd(&(bar)[XB_TMO], 1u); break; } } } } while (0)
; __device__ __forceinline__ void xcd_barrier(const XcdBarrier& b) {
;     ...
;             if (og + 1u == (tg + 1u) * nx) xb_add(&bar[XB_TOPGEN], 1u);
;             else XB_SPIN(xb_ld(&bar[XB_TOPGEN]) == tg, bar);
;             __builtin_amdgcn_fence(__ATOMIC_ACQUIRE, "agent");
;             xb_add(&bar[XB_XGEN(b.x)], 1u);
.LBB0_968:
	s_or_b64 exec, exec, s[12:13]
	s_mov_b64 s[12:13], exec
	v_mbcnt_lo_u32_b32 v0, s12, 0
	v_mbcnt_hi_u32_b32 v0, s13, v0
	v_cmp_eq_u32_e32 vcc, 0, v0
	s_waitcnt vmcnt(0)
	s_and_saveexec_b64 s[14:15], vcc
	s_cbranch_execz .LBB0_970
	s_bcnt1_i32_b64 s12, s[12:13]
	v_mov_b32_e32 v0, 0x2000
	v_mov_b32_e32 v1, s12
	global_atomic_add v0, v1, s[8:9] offset:1024

; __device__ __forceinline__ void xcd_barrier(const XcdBarrier& b) {
;     asm volatile("s_waitcnt vmcnt(0)" ::: "memory");
;     __syncthreads();
;     if (threadIdx.x == 0) {
;         unsigned* bar = b.bar;
;         __builtin_amdgcn_s_waitcnt(0);
;         unsigned nloc = b.st[0], nx = b.st[1];
;         if (nloc == 0u) { xcd_barrier_complete(bar, b.x, nloc, nx); b.st[0] = nloc; b.st[1] = nx; }
.LBB0_977:
	s_or_b64 exec, exec, s[12:13]
	s_waitcnt vmcnt(0)
	s_barrier
	s_mov_b64 s[6:7], exec
	v_readlane_b32 s8, v255, 3
	v_readlane_b32 s9, v255, 4
	s_and_b64 s[8:9], s[6:7], s[8:9]
	s_mov_b64 exec, s[8:9]
	s_cbranch_execz .LBB0_1028
	s_add_i32 s8, 0, 0x20000
	v_mov_b32_e32 v0, s8
	s_waitcnt vmcnt(0) expcnt(0) lgkmcnt(0)
	buffer_inv sc1
	ds_read_b32 v2, v0
	s_add_i32 s8, 0, 0x20004
	v_mov_b32_e32 v0, s8
	ds_read_b32 v0, v0
	s_mov_b32 s15, 0
	s_waitcnt lgkmcnt(1)
	v_cmp_ne_u32_e32 vcc, 0, v2
	s_cbranch_vccnz .LBB0_992
	s_load_dword s8, s[0:1], 0xc8
	v_readlane_b32 s10, v255, 2
	v_mov_b32_e32 v1, 0
	s_waitcnt lgkmcnt(0)
	s_mul_i32 s16, s29, s8
	s_add_u32 s8, s90, 0x32200
	s_addc_u32 s9, s91, 0
	s_lshl_b32 s17, s10, 8
	s_add_u32 s18, s90, 0x32400
	s_mul_i32 s16, s16, s28
	s_addc_u32 s19, s91, 0
	s_branch .LBB0_981
